# barrier: non-leader workgroups poll the top-level generation word instead of the per-XCD one
# speedup vs baseline: 1.0010x; 1.0010x over previous
; __device__ __forceinline__ unsigned xb_ld(unsigned* p)              { return __hip_atomic_load(p, __ATOMIC_RELAXED, __HIP_MEMORY_SCOPE_AGENT); }
; __device__ __forceinline__ unsigned xb_add(unsigned* p, unsigned v) { return __hip_atomic_fetch_add(p, v, __ATOMIC_RELAXED, __HIP_MEMORY_SCOPE_AGENT); }
; #define XB_SPIN(cond, bar) do { unsigned _sp = 0; while (cond) { __builtin_amdgcn_s_sleep(1); \
;     if ((++_sp & 255u) == 0u) { if (xb_ld(&(bar)[XB_TMO])) break; if (_sp > XB_SPIN_CAP) { atomicAdd(&(bar)[XB_TMO], 1u); break; } } } } while (0)
; __device__ __forceinline__ void xcd_barrier(const XcdBarrier& b) {
;     ...
;         const unsigned old = xb_add(&bar[XB_XSUB(b.x)], 1u);
;         const unsigned gen = old / nloc;
;         if (old + 1u == (gen + 1u) * nloc) {
;             __builtin_amdgcn_fence(__ATOMIC_RELEASE, "agent");
;             asm volatile("s_waitcnt vmcnt(0)" ::: "memory");
;             const unsigned og = xb_add(&bar[XB_TOP], 1u);
;             const unsigned tg = og / nx;
;             if (og + 1u == (tg + 1u) * nx) xb_add(&bar[XB_TOPGEN], 1u);
;             else XB_SPIN(xb_ld(&bar[XB_TOPGEN]) == tg, bar);
;             __builtin_amdgcn_fence(__ATOMIC_ACQUIRE, "agent");
;             xb_add(&bar[XB_XGEN(b.x)], 1u);
;             asm volatile("s_waitcnt vmcnt(0)" ::: "memory");
;         } else {
;             XB_SPIN(xb_ld(&bar[XB_XGEN(b.x)]) == gen, bar);
.LBB0_1387:
	s_or_b64 exec, exec, s[12:13]
	v_cvt_f32_u32_e32 v4, v2
	s_waitcnt vmcnt(0)
	v_readfirstlane_b32 s3, v3
	v_sub_u32_e32 v3, 0, v2
	v_rcp_iflag_f32_e32 v4, v4
	v_add_u32_e32 v5, s3, v1
	v_mul_f32_e32 v4, 0x4f7ffffe, v4
	v_cvt_u32_f32_e32 v4, v4
	v_mul_lo_u32 v1, v3, v4
	v_mul_hi_u32 v1, v4, v1
	v_add_u32_e32 v1, v4, v1
	v_mul_hi_u32 v1, v5, v1
	v_mul_lo_u32 v3, v1, v2
	v_sub_u32_e32 v3, v5, v3
	v_add_u32_e32 v4, 1, v1
	v_cmp_ge_u32_e32 vcc, v3, v2
	s_nop 1
	v_cndmask_b32_e32 v1, v1, v4, vcc
	v_sub_u32_e32 v4, v3, v2
	v_cndmask_b32_e32 v3, v3, v4, vcc
	v_add_u32_e32 v4, 1, v1
	v_cmp_ge_u32_e32 vcc, v3, v2
	v_add_u32_e32 v3, 1, v5
	s_nop 0
	v_cndmask_b32_e32 v1, v1, v4, vcc
	v_mul_lo_u32 v4, v2, v1
	v_add_u32_e32 v2, v4, v2
	v_cmp_ne_u32_e32 vcc, v3, v2
	s_and_saveexec_b64 s[10:11], vcc
	s_xor_b64 s[10:11], exec, s[10:11]
	s_cbranch_execz .LBB0_1401
	s_waitcnt lgkmcnt(0)
	v_mov_b32_e32 v0, 0x3089100
	global_load_dword v0, v0, s[54:55] sc1
	s_add_u32 s16, s54, 0x3089100
	s_addc_u32 s17, s55, 0
	s_waitcnt vmcnt(0)
	v_cmp_eq_u32_e32 vcc, v0, v1
	s_and_saveexec_b64 s[12:13], vcc
	s_cbranch_execz .LBB0_1400
	s_add_u32 s14, s54, 0x3085e00
	s_addc_u32 s15, s55, 0
	s_mov_b32 s3, 1
	s_mov_b64 s[18:19], 0
	v_mov_b32_e32 v0, 0
	s_branch .LBB0_1391
